# front tile split totals 2/4/6/7 (pass-2 2/2/3/4)
# baseline (speedup 1.0000x reference)
.LBB0_155:
	s_or_b64 exec, exec, s[0:1]
	s_mov_b32 s100, 1
	s_lshr_b32 s0, s83, 6
	s_and_b32 s1, s83, 63
	s_movk_i32 s4, 2
	s_movk_i32 s5, 512
	s_cmp_eq_u32 s0, 1
	s_cselect_b32 s4, 2, s4
	s_cselect_b32 s5, 640, s5
	s_cmp_eq_u32 s0, 2
	s_cselect_b32 s4, 3, s4
	s_cselect_b32 s5, 768, s5
	s_cmp_eq_u32 s0, 3
	s_cselect_b32 s4, 4, s4
	s_cselect_b32 s5, 960, s5
	s_mul_i32 s6, s1, s4
	s_add_i32 s8, s5, s6
	s_add_i32 s10, s8, s4
	s_cmp_eq_u32 s4, 0
	s_cbranch_scc1 .Lp0_second_done
	s_mul_i32 s3, s62, 0x2080
	s_mov_b32 s33, s3
	s_branch .LBB0_34
